# diff attention: next tile's K fragments prefetched from LDS during the PV MFMAs (K staged two tiles ahead by LDS-DMA); DMA issue moved behind first QK MFMAs
# speedup vs baseline: 1.0024x; 1.0024x over previous
; template <int KIND> ...
;     ...
;                 for (int t4 = 0; t4 < 4; ++t4) { kf[2 * t4] = *(const LAS bf16x8*)(lds + buf * KBUF + koff + 32 * t4); kf[2 * t4 + 1] = *(const LAS bf16x8*)(lds + buf * KBUF + koff + 32 * KSTR + 32 * t4); }
;                 __builtin_amdgcn_sched_barrier(0);
;                 f32x16 s0, s1;
; #pragma unroll
;                 for (int t4 = 0; t4 < 4; ++t4) {
;                     s0 = __builtin_amdgcn_mfma_f32_32x32x16_bf16(kf[2 * t4], qf[t4], t4 == 0 ? mneg : s0, 0, 0, 0);
;                     s1 = __builtin_amdgcn_mfma_f32_32x32x16_bf16(kf[2 * t4 + 1], qf[t4], t4 == 0 ? mneg : s1, 0, 0, 0);
;                 }
;                 float ab0[16], ab1[16];
;                 const bool na_lat = (KIND == 0) && (t < n1);
;                 if (na_lat) {
;                     const int bo = boff0 + (kr_lo + t - qr + 7) * 124;
; #pragma unroll
;                     for (int j = 0; j < 16; ++j) {
;                         const int C0 = 8 * (j >> 2) + (j & 3), C1 = 32 + C0;
;                         const float b0 = *(const LAS float*)(lds + bo + 4 * C0), b1 = *(const LAS float*)(lds + bo + 4 * C1);
;                         ab0[j] = ((unsigned)(wb + C0) < 16u) ? b0 : -1e30f;
;                         ab1[j] = ((unsigned)(wb + C1) < 16u) ? b1 : -1e30f;
;                     }
; #pragma unroll
;                     for (int i = 0; i < 8; ++i) { __builtin_amdgcn_sched_group_barrier(0x008, 1, 0); __builtin_amdgcn_sched_group_barrier(0x100, 4, 0); __builtin_amdgcn_sched_group_barrier(0x002, 12, 0); }
;                 }
;                 __builtin_amdgcn_sched_barrier(0);
;                 s16x4 vfa[2][NDT][2], vfb[2][NDT][2];
; #pragma unroll
;                 for (int s = 0; s < 2; ++s)
; #pragma unroll
;                     for (int dt = 0; dt < NDT; ++dt) {
;                         vfa[s][dt][0] = __builtin_amdgcn_ds_read_tr16_b64_v4i16((LAS s16x4*)(lds + buf * VBUF + voff + (16 * s) * VSTR + 64 * dt));
;                         vfa[s][dt][1] = __builtin_amdgcn_ds_read_tr16_b64_v4i16((LAS s16x4*)(lds + buf * VBUF + voff + (16 * s + 8) * VSTR + 64 * dt)); }
;                 __builtin_amdgcn_sched_barrier(0);
;                 if (na_lat) {
; #pragma unroll
;                     for (int j = 0; j < 16; ++j) { s0[j] += ab0[j]; s1[j] += ab1[j]; }
;                 }
;                 const float mx0 = fmaxf(s1[15], s0[15]);
.LBB0_187:
	s_add_i32 s14, s14, s21
	s_and_b32 s26, s26, 7
	v_add_u32_e32 v2, s14, v199
	v_mov_b64_e32 v[0:1], s[58:59]
	s_movk_i32 s34, 0x1800
	s_lshl_b32 s28, s26, 6
	v_mad_i64_i32 v[2:3], s[4:5], v2, s34, v[0:1]
	s_or_b32 s4, s28, s22
	s_lshl_b32 s96, s26, 7
	s_add_i32 s15, s27, 0x8000
	s_ashr_i32 s5, s4, 31
	v_lshl_add_u64 v[2:3], s[4:5], 1, v[2:3]
	s_and_b64 s[4:5], s[16:17], exec
	v_lshl_add_u64 v[2:3], v[202:203], 1, v[2:3]
	s_cselect_b32 s30, s2, s15
	global_load_dwordx4 v[128:131], v[2:3], off
	global_load_dwordx4 v[132:135], v[2:3], off offset:32
	global_load_dwordx4 v[136:139], v[2:3], off offset:64
	global_load_dwordx4 v[140:143], v[2:3], off offset:96
	s_lshl_b32 s4, s26, 8
	s_add_u32 s4, s58, s4
	s_addc_u32 s5, s59, 0
	s_add_u32 s4, s4, 0x1000
	s_addc_u32 s5, s5, 0
	v_lshl_add_u64 v[210:211], v[204:205], 0, s[96:97]
	v_mov_b64_e32 v[16:17], s[4:5]
	s_or_b32 s26, s3, 4
	s_or_b32 s28, s2, 64
	s_add_i32 s27, s27, 0x8040
	s_and_b64 s[16:17], s[16:17], exec
	s_cselect_b32 s27, s28, s27
	v_add_u32_e32 v0, s30, v226
	v_mad_i64_i32 v[0:1], vcc, v0, s34, v[210:211]
	s_mov_b32 m0, s18
	v_add_u32_e32 v2, s30, v237
	global_load_lds_dwordx4 v[0:1], off
	s_add_i32 m0, s18, 0x1c00
	v_mad_i64_i32 v[2:3], vcc, v2, s34, v[16:17]
	global_load_lds_dwordx4 v[0:1], off offset:1024
	v_lshl_add_u64 v[2:3], v[2:3], 0, v[206:207]
	s_add_i32 m0, s18, 0x8000
	v_add_u32_e32 v4, s30, v238
	global_load_lds_dwordx4 v[2:3], off
	v_mad_i64_i32 v[4:5], vcc, v4, s34, v[16:17]
	v_lshl_add_u64 v[4:5], v[4:5], 0, v[208:209]
	s_add_i32 m0, s18, 0xa000
	s_nop 0
	global_load_lds_dwordx4 v[4:5], off
	v_add_u32_e32 v0, s27, v226
	v_mad_i64_i32 v[0:1], vcc, v0, s34, v[210:211]
	s_add_i32 m0, s18, 0x4000
	s_nop 0
	global_load_lds_dwordx4 v[0:1], off
	s_add_i32 m0, s18, 0x5c00
	s_nop 0
	global_load_lds_dwordx4 v[0:1], off offset:1024
	s_waitcnt vmcnt(0)
	s_barrier
	v_add_u32_e32 v2, s27, v237
	v_mad_i64_i32 v[2:3], vcc, v2, s34, v[16:17]
	v_lshl_add_u64 v[2:3], v[2:3], 0, v[206:207]
	s_add_i32 m0, s18, 0xc000
	v_add_u32_e32 v4, s27, v238
	global_load_lds_dwordx4 v[2:3], off
	v_mad_i64_i32 v[4:5], vcc, v4, s34, v[16:17]
	v_lshl_add_u64 v[4:5], v[4:5], 0, v[208:209]
	s_add_i32 m0, s18, 0xe000
	s_nop 0
	global_load_lds_dwordx4 v[4:5], off
	v_xor_b32_e32 v144, 32, v235
	v_xor_b32_e32 v145, 64, v235
	v_xor_b32_e32 v146, 0x60, v235
	v_xor_b32_e32 v147, 64, v236
	v_xor_b32_e32 v148, 0x80, v236
	v_xor_b32_e32 v149, 0xc0, v236
	ds_read_b128 v[16:19], v235 offset:4096
	ds_read_b128 v[0:3], v235
	ds_read_b128 v[32:35], v144
	ds_read_b128 v[36:39], v144 offset:4096
	ds_read_b128 v[40:43], v145
	ds_read_b128 v[44:47], v145 offset:4096
	ds_read_b128 v[48:51], v146
	ds_read_b128 v[52:55], v146 offset:4096
	s_waitcnt lgkmcnt(6)
	v_mfma_f32_32x32x16_bf16 v[0:15], v[0:3], v[128:131], 0
	ds_read_b64_tr_b16 v[112:113], v148 offset:32768
	ds_read_b64_tr_b16 v[116:117], v149 offset:32768
	ds_read_b64_tr_b16 v[114:115], v148 offset:34816
	ds_read_b64_tr_b16 v[118:119], v149 offset:34816
	ds_read_b64_tr_b16 v[108:109], v236 offset:36864
	ds_read_b64_tr_b16 v[104:105], v147 offset:36864
	ds_read_b64_tr_b16 v[100:101], v148 offset:36864
	v_mfma_f32_32x32x16_bf16 v[16:31], v[16:19], v[128:131], 0
	ds_read_b64_tr_b16 v[96:97], v149 offset:36864
	ds_read_b64_tr_b16 v[110:111], v236 offset:38912
	ds_read_b64_tr_b16 v[106:107], v147 offset:38912
	ds_read_b64_tr_b16 v[102:103], v148 offset:38912
	ds_read_b64_tr_b16 v[98:99], v149 offset:38912
	s_waitcnt lgkmcnt(14)
	v_mfma_f32_32x32x16_bf16 v[0:15], v[32:35], v[132:135], v[0:15]
	ds_read_b64_tr_b16 v[32:33], v236 offset:32768
	ds_read_b64_tr_b16 v[34:35], v236 offset:34816
	v_mfma_f32_32x32x16_bf16 v[16:31], v[36:39], v[132:135], v[16:31]
	ds_read_b64_tr_b16 v[36:37], v147 offset:32768
	ds_read_b64_tr_b16 v[38:39], v147 offset:34816
	v_mfma_f32_32x32x16_bf16 v[0:15], v[40:43], v[136:139], v[0:15]
	v_mfma_f32_32x32x16_bf16 v[16:31], v[44:47], v[136:139], v[16:31]
	s_waitcnt lgkmcnt(14)
	v_mfma_f32_32x32x16_bf16 v[0:15], v[48:51], v[140:143], v[0:15]
	v_mfma_f32_32x32x16_bf16 v[16:31], v[52:55], v[140:143], v[16:31]
	s_nop 10
	v_max_f32_e32 v40, v15, v15
	v_max_f32_e32 v41, v31, v31
	v_max_f32_e32 v40, v41, v40
	v_max3_f32 v41, v40, v0, v16
	v_max3_f32 v40, v40, v1, v17
	s_nop 0
	v_max3_f32 v41, v41, v2, v18
	v_max3_f32 v40, v40, v3, v19
	s_nop 0
	v_max3_f32 v41, v41, v4, v20
	v_max3_f32 v40, v40, v5, v21
	s_nop 0
	v_max3_f32 v41, v41, v6, v22
	v_max3_f32 v40, v40, v7, v23
	s_nop 0
	v_max3_f32 v41, v41, v8, v24
	v_max3_f32 v40, v40, v9, v25
	s_nop 0
	v_max3_f32 v41, v41, v10, v26
	v_max3_f32 v40, v40, v11, v27
	s_nop 0
	v_max3_f32 v41, v41, v12, v28
	v_max3_f32 v40, v40, v13, v29
	s_nop 0
	v_max3_f32 v41, v41, v14, v30
	v_max3_f32 v40, v40, v15, v31
	s_nop 0
	v_max_f32_e32 v40, v40, v40
	v_max_f32_e32 v41, v41, v41
	v_max_f32_e32 v40, v41, v40
	ds_bpermute_b32 v41, v197, v40
	s_waitcnt lgkmcnt(0)
	v_max_f32_e32 v41, v41, v41
	v_max_f32_e32 v40, v40, v41
	v_sub_f32_e32 v0, v0, v40
	v_sub_f32_e32 v1, v1, v40
	v_sub_f32_e32 v2, v2, v40
	v_sub_f32_e32 v3, v3, v40
	v_sub_f32_e32 v4, v4, v40
	v_sub_f32_e32 v5, v5, v40
	v_sub_f32_e32 v6, v6, v40
	v_sub_f32_e32 v7, v7, v40
	v_sub_f32_e32 v8, v8, v40
	v_sub_f32_e32 v9, v9, v40
	v_sub_f32_e32 v10, v10, v40
	v_sub_f32_e32 v11, v11, v40
	v_sub_f32_e32 v12, v12, v40
	v_sub_f32_e32 v13, v13, v40
	v_sub_f32_e32 v14, v14, v40
	v_sub_f32_e32 v15, v15, v40
	v_exp_f32_e32 v0, v0
	v_exp_f32_e32 v1, v1
	v_exp_f32_e32 v2, v2
	v_exp_f32_e32 v3, v3
	v_exp_f32_e32 v4, v4
	v_exp_f32_e32 v5, v5
	v_exp_f32_e32 v6, v6
	v_exp_f32_e32 v7, v7
	v_exp_f32_e32 v8, v8
	v_exp_f32_e32 v9, v9
	v_exp_f32_e32 v10, v10
	v_exp_f32_e32 v11, v11
	v_exp_f32_e32 v12, v12
	v_exp_f32_e32 v13, v13
	v_exp_f32_e32 v14, v14
	v_exp_f32_e32 v15, v15
	v_sub_f32_e32 v64, 0, v40
	v_sub_f32_e32 v16, v16, v40
	v_sub_f32_e32 v17, v17, v40
	v_sub_f32_e32 v18, v18, v40
	v_sub_f32_e32 v19, v19, v40
	v_sub_f32_e32 v20, v20, v40
	v_sub_f32_e32 v21, v21, v40
	v_sub_f32_e32 v22, v22, v40
	v_sub_f32_e32 v23, v23, v40
	v_sub_f32_e32 v24, v24, v40
	v_mov_b32_e32 v65, v64
	v_mov_b32_e32 v66, v64
	v_mov_b32_e32 v67, v64
	v_mov_b32_e32 v68, v64
	v_mov_b32_e32 v69, v64
	v_mov_b32_e32 v70, v64
	v_mov_b32_e32 v71, v64
	v_mov_b32_e32 v72, v64
	v_mov_b32_e32 v73, v64
	v_mov_b32_e32 v74, v64
	v_mov_b32_e32 v75, v64
	v_mov_b32_e32 v76, v64
	v_mov_b32_e32 v77, v64
	v_mov_b32_e32 v78, v64
	v_mov_b32_e32 v79, v64
	v_cvt_pk_bf16_f32 v0, v0, v1
	v_cvt_pk_bf16_f32 v1, v2, v3
	v_cvt_pk_bf16_f32 v2, v4, v5
	v_cvt_pk_bf16_f32 v3, v6, v7
	v_sub_f32_e32 v160, v25, v40
	v_sub_f32_e32 v161, v26, v40
	v_sub_f32_e32 v162, v27, v40
	v_sub_f32_e32 v163, v28, v40
	v_sub_f32_e32 v164, v29, v40
	v_sub_f32_e32 v165, v30, v40
	v_sub_f32_e32 v166, v31, v40
	v_cvt_pk_bf16_f32 v120, v8, v9
	v_cvt_pk_bf16_f32 v121, v10, v11
	v_cvt_pk_bf16_f32 v122, v12, v13
	v_cvt_pk_bf16_f32 v123, v14, v15
	s_barrier
; template <int KIND> ...
;     ...
;                 __builtin_amdgcn_sched_barrier(0);
; #pragma unroll
;                 for (int s = 0; s < 2; ++s)
; #pragma unroll
;                     for (int dt = 0; dt < NDT; ++dt) {
;                         vfb[s][dt][0] = __builtin_amdgcn_ds_read_tr16_b64_v4i16((LAS s16x4*)(lds + buf * VBUF + voff + (16 * (s + 2)) * VSTR + 64 * dt));
;                         vfb[s][dt][1] = __builtin_amdgcn_ds_read_tr16_b64_v4i16((LAS s16x4*)(lds + buf * VBUF + voff + (16 * (s + 2) + 8) * VSTR + 64 * dt)); }
;                 {
;                     constexpr int NM = 2 * (1 + NDT);
;                     int mi = 0;
; #pragma unroll
;                     for (int s = 0; s < 2; ++s) {
;                         lacc = __builtin_amdgcn_mfma_f32_32x32x16_bf16(ones, pf[s], lacc, 0, 0, 0);
; #pragma unroll
;                         for (int j = (mi * 16) / NM; j < ((mi + 1) * 16) / NM; ++j) s1[j] = __builtin_amdgcn_exp2f(s1[j]);
;                         ++mi;
; #pragma unroll
;                         for (int dt = 0; dt < NDT; ++dt) {
;                             const s16x4 va = vfa[s][dt][0], vb = vfa[s][dt][1];
;                             const bf16x8 vf = {va[0], va[1], va[2], va[3], vb[0], vb[1], vb[2], vb[3]};
;                             o[dt] = __builtin_amdgcn_mfma_f32_32x32x16_bf16(vf, pf[s], o[dt], 0, 0, 0);
; #pragma unroll
;                             for (int j = (mi * 16) / NM; j < ((mi + 1) * 16) / NM; ++j) s1[j] = __builtin_amdgcn_exp2f(s1[j]);
;                             ++mi;
;                         }
;                     }
; #pragma unroll
;                     for (int q = 0; q < 2; ++q) { u32x4 w; w.x = pk2n(s1[8 * q + 0], s1[8 * q + 1]); w.y = pk2n(s1[8 * q + 2], s1[8 * q + 3]); w.z = pk2n(s1[8 * q + 4], s1[8 * q + 5]); w.w = pk2n(s1[8 * q + 6], s1[8 * q + 7]);
;                         pf[q + 2] = __builtin_bit_cast(bf16x8, w); }
; #pragma unroll
;                     for (int i = 0; i < NM; ++i) { __builtin_amdgcn_sched_group_barrier(0x008, 1, 0); __builtin_amdgcn_sched_group_barrier(0x402, (16 + NM - 1) / NM + 1, 0); }
;                 }
;                 __builtin_amdgcn_sched_barrier(0);
; #pragma unroll
;                 for (int s = 0; s < 2; ++s) {
;                     lacc = __builtin_amdgcn_mfma_f32_32x32x16_bf16(ones, pf[s + 2], lacc, 0, 0, 0);
; #pragma unroll
	s_cmp_gt_u32 s3, 2
	s_cselect_b32 s29, 0, s3
	s_cselect_b32 s28, s2, s15
	s_lshl_b32 s29, s29, 6
	s_sub_i32 s29, s28, s29
	v_add_u32_e32 v154, s29, v245
	v_mad_i64_i32 v[154:155], vcc, v154, s34, v[210:211]
	s_mov_b32 m0, s18
	s_nop 0
	global_load_lds_dwordx4 v[154:155], off
	s_add_i32 m0, s18, 0x1c00
	s_nop 0
	global_load_lds_dwordx4 v[154:155], off offset:1024
	v_mfma_f32_32x32x16_bf16 v[48:63], v[32:35], v[0:3], 0
	v_mov_b64_e32 v[126:127], s[86:87]
	v_mov_b64_e32 v[124:125], s[84:85]
	v_exp_f32_e32 v167, v16
	s_nop 0
	v_mfma_f32_32x32x16_bf16 v[80:95], v[124:127], v[0:3], 0
	v_exp_f32_e32 v168, v17
	v_exp_f32_e32 v169, v18
	v_exp_f32_e32 v170, v19
	v_mfma_f32_32x32x16_bf16 v[32:47], v[36:39], v[0:3], 0
	v_exp_f32_e32 v171, v20
	v_exp_f32_e32 v172, v21
	v_exp_f32_e32 v173, v22
	v_mfma_f32_32x32x16_bf16 v[80:95], v[124:127], v[120:123], v[80:95]
	v_exp_f32_e32 v174, v23
	v_exp_f32_e32 v175, v24
	v_exp_f32_e32 v176, v160
	v_mfma_f32_32x32x16_bf16 v[16:31], v[112:115], v[0:3], 0
	v_exp_f32_e32 v177, v161
	v_exp_f32_e32 v178, v162
	v_exp_f32_e32 v179, v163
	ds_read_b64_tr_b16 v[112:113], v236 offset:40960
	ds_read_b64_tr_b16 v[114:115], v236 offset:43008
	ds_read_b64_tr_b16 v[160:161], v148 offset:40960
	ds_read_b64_tr_b16 v[162:163], v148 offset:43008
	v_mfma_f32_32x32x16_bf16 v[0:15], v[116:119], v[0:3], 0
	v_exp_f32_e32 v180, v164
	v_exp_f32_e32 v181, v166
	v_exp_f32_e32 v182, v165
	v_mfma_f32_32x32x16_bf16 v[48:63], v[108:111], v[120:123], v[48:63]
	v_cvt_pk_bf16_f32 v116, v167, v168
	v_cvt_pk_bf16_f32 v117, v169, v170
	v_cvt_pk_bf16_f32 v118, v171, v172
	ds_read_b64_tr_b16 v[108:109], v147 offset:40960
	ds_read_b64_tr_b16 v[110:111], v147 offset:43008
	ds_read_b64_tr_b16 v[168:169], v236 offset:45056
	ds_read_b64_tr_b16 v[170:171], v236 offset:47104
	v_mfma_f32_32x32x16_bf16 v[32:47], v[104:107], v[120:123], v[32:47]
	v_cvt_pk_bf16_f32 v119, v173, v174
	v_cvt_pk_bf16_f32 v164, v175, v176
	v_cvt_pk_bf16_f32 v165, v177, v178
	ds_read_b64_tr_b16 v[104:105], v149 offset:40960
	ds_read_b64_tr_b16 v[106:107], v149 offset:43008
	ds_read_b64_tr_b16 v[172:173], v148 offset:45056
	ds_read_b64_tr_b16 v[174:175], v148 offset:47104
	v_mfma_f32_32x32x16_bf16 v[16:31], v[100:103], v[120:123], v[16:31]
	v_cvt_pk_bf16_f32 v166, v179, v180
	v_cvt_pk_bf16_f32 v167, v182, v181
	ds_read_b64_tr_b16 v[100:101], v147 offset:45056
	ds_read_b64_tr_b16 v[102:103], v147 offset:47104
	ds_read_b64_tr_b16 v[176:177], v149 offset:45056
	ds_read_b64_tr_b16 v[178:179], v149 offset:47104
	v_mfma_f32_32x32x16_bf16 v[0:15], v[96:99], v[120:123], v[0:15]
	v_mfma_f32_32x32x16_bf16 v[80:95], v[124:127], v[116:119], v[80:95]
	s_waitcnt lgkmcnt(14)
	v_mfma_f32_32x32x16_bf16 v[48:63], v[112:115], v[116:119], v[48:63]
	s_waitcnt lgkmcnt(10)
	v_mfma_f32_32x32x16_bf16 v[32:47], v[108:111], v[116:119], v[32:47]
	v_mfma_f32_32x32x16_bf16 v[16:31], v[160:163], v[116:119], v[16:31]
	s_waitcnt lgkmcnt(6)
	v_mfma_f32_32x32x16_bf16 v[0:15], v[104:107], v[116:119], v[0:15]
	v_mfma_f32_32x32x16_bf16 v[80:95], v[124:127], v[164:167], v[80:95]
	v_mfma_f32_32x32x16_bf16 v[48:63], v[168:171], v[164:167], v[48:63]
	s_waitcnt lgkmcnt(2)
	v_mfma_f32_32x32x16_bf16 v[32:47], v[100:103], v[164:167], v[32:47]
	v_mfma_f32_32x32x16_bf16 v[16:31], v[172:175], v[164:167], v[16:31]
	s_waitcnt lgkmcnt(0)
	v_mfma_f32_32x32x16_bf16 v[0:15], v[176:179], v[164:167], v[0:15]
	v_lshl_add_u64 v[212:213], s[4:5], 0, v[206:207]
	v_lshl_add_u64 v[214:215], s[4:5], 0, v[208:209]
	s_mov_b32 s16, -3
	v_mov_b32_e32 v248, v245
	v_mov_b32_e32 v249, v244
	v_mov_b32_e32 v250, v243
	v_add_u32_e32 v150, 0x4000, v235
	v_xor_b32_e32 v151, 32, v150
	v_xor_b32_e32 v152, 64, v150
	v_xor_b32_e32 v153, 0x60, v150
	ds_read_b128 v[96:99], v150
	ds_read_b128 v[160:163], v151
	ds_read_b128 v[164:167], v150 offset:4096
	ds_read_b128 v[168:171], v151 offset:4096
	ds_read_b128 v[172:175], v152
	ds_read_b128 v[218:221], v153
	ds_read_b128 v[176:179], v152 offset:4096
	ds_read_b128 v[230:233], v153 offset:4096
	s_waitcnt vmcnt(0)
	s_waitcnt lgkmcnt(0)
	s_barrier
	s_branch .LBB0_189

; #define LAS __attribute__((address_space(3)))
; template <int KIND> ...
;     ...
;             if (t + 1 < nt) ATT_LOAD(t + 1);
;             bool active = true;
;             if (KIND == 0 && t < n1) { const int kr = kr_lo + t; active = (kr >= rs_w) && (kr < rs_w + 8); }
;             if (__builtin_amdgcn_readfirstlane((int)active)) {
;                 const int buf = t & 1;
;                 bf16x8 kf[8];
; #pragma unroll
;                 for (int t4 = 0; t4 < 4; ++t4) { kf[2 * t4] = *(const LAS bf16x8*)(lds + buf * KBUF + koff + 32 * t4); kf[2 * t4 + 1] = *(const LAS bf16x8*)(lds + buf * KBUF + koff + 32 * KSTR + 32 * t4); }
;                 __builtin_amdgcn_sched_barrier(0);
;                 f32x16 s0, s1;
; #pragma unroll
;                 for (int t4 = 0; t4 < 4; ++t4) {
;                     s0 = __builtin_amdgcn_mfma_f32_32x32x16_bf16(kf[2 * t4], qf[t4], t4 == 0 ? mneg : s0, 0, 0, 0);
;                     s1 = __builtin_amdgcn_mfma_f32_32x32x16_bf16(kf[2 * t4 + 1], qf[t4], t4 == 0 ? mneg : s1, 0, 0, 0);
;                 }
;                 float ab0[16], ab1[16];
;                 const bool na_lat = (KIND == 0) && (t < n1);
;                 if (na_lat) {
;                     const int bo = boff0 + (kr_lo + t - qr + 7) * 124;
; #pragma unroll
;                     for (int j = 0; j < 16; ++j) {
;                         const int C0 = 8 * (j >> 2) + (j & 3), C1 = 32 + C0;
;                         const float b0 = *(const LAS float*)(lds + bo + 4 * C0), b1 = *(const LAS float*)(lds + bo + 4 * C1);
;                         ab0[j] = ((unsigned)(wb + C0) < 16u) ? b0 : -1e30f;
;                         ab1[j] = ((unsigned)(wb + C1) < 16u) ? b1 : -1e30f;
;                     }
; #pragma unroll
;                     for (int i = 0; i < 8; ++i) { __builtin_amdgcn_sched_group_barrier(0x008, 1, 0); __builtin_amdgcn_sched_group_barrier(0x100, 4, 0); __builtin_amdgcn_sched_group_barrier(0x002, 12, 0); }
;                 }
;                 __builtin_amdgcn_sched_barrier(0);
;                 s16x4 vfa[2][NDT][2], vfb[2][NDT][2];
; #pragma unroll
;                 for (int s = 0; s < 2; ++s)
; #pragma unroll
;                     for (int dt = 0; dt < NDT; ++dt) {
;                         vfa[s][dt][0] = __builtin_amdgcn_ds_read_tr16_b64_v4i16((LAS s16x4*)(lds + buf * VBUF + voff + (16 * s) * VSTR + 64 * dt));
.LBB0_191:
	s_add_i32 s27, s16, 4
	s_and_b32 s27, s27, 1
	s_waitcnt lgkmcnt(7)
	v_mfma_f32_32x32x16_bf16 v[112:127], v[96:99], v[128:131], v[64:79]
	s_lshl_b32 s27, s27, 14
	v_add_u32_e32 v251, s27, v236
	v_xor_b32_e32 v147, 64, v251
	v_xor_b32_e32 v148, 0x80, v251
	v_xor_b32_e32 v149, 0xc0, v251
	s_waitcnt lgkmcnt(5)
	v_mfma_f32_32x32x16_bf16 v[96:111], v[164:167], v[128:131], v[64:79]
	v_mfma_f32_32x32x16_bf16 v[112:127], v[160:163], v[132:135], v[112:127]
	s_waitcnt lgkmcnt(4)
	v_mfma_f32_32x32x16_bf16 v[96:111], v[168:171], v[132:135], v[96:111]
	s_cmp_ge_u32 s17, s26
	s_cbranch_scc1 .Ldf4_noL
	s_cmp_lt_u32 s17, s3
	s_cselect_b32 s35, 0, s3
	s_cselect_b32 s28, s2, s15
	s_lshl_b32 s35, s35, 6
	s_sub_i32 s35, s28, s35
	s_movk_i32 s30, 0x1800
	s_and_b32 s29, s17, 1
	s_lshl_b32 s29, s29, 14
	s_add_i32 s29, s29, s18
	v_add_u32_e32 v154, s35, v249
	v_mad_i64_i32 v[154:155], vcc, v154, s30, v[212:213]
	s_add_i32 m0, s29, 0x8000
	v_add_u32_e32 v156, s35, v250
	global_load_lds_dwordx4 v[154:155], off
	v_mad_i64_i32 v[156:157], vcc, v156, s30, v[214:215]
	s_add_i32 m0, s29, 0xa000
	s_nop 0
	global_load_lds_dwordx4 v[156:157], off
	s_add_i32 s36, s17, 1
	s_cmp_ge_u32 s36, s26
	s_cbranch_scc1 .Ldf4_noL
	s_cmp_lt_u32 s36, s3
	s_cselect_b32 s35, 0, s3
	s_cselect_b32 s28, s2, s15
	s_lshl_b32 s35, s35, 6
	s_sub_i32 s35, s28, s35
	s_add_i32 s35, s35, 64
	s_xor_b32 s29, s29, 0x4000
	v_add_u32_e32 v154, s35, v248
	v_mad_i64_i32 v[154:155], vcc, v154, s30, v[210:211]
	s_mov_b32 m0, s29
	s_nop 0
	global_load_lds_dwordx4 v[154:155], off
	s_add_i32 m0, s29, 0x1c00
	s_nop 0
	global_load_lds_dwordx4 v[154:155], off offset:1024
.Ldf4_noL:
	s_waitcnt lgkmcnt(3)
	v_mfma_f32_32x32x16_bf16 v[112:127], v[172:175], v[136:139], v[112:127]
	s_waitcnt lgkmcnt(1)
	v_mfma_f32_32x32x16_bf16 v[96:111], v[176:179], v[136:139], v[96:111]
	ds_read_b64_tr_b16 v[188:189], v251 offset:32768
	ds_read_b64_tr_b16 v[184:185], v147 offset:32768
	ds_read_b64_tr_b16 v[180:181], v148 offset:32768
	ds_read_b64_tr_b16 v[176:177], v149 offset:32768
	ds_read_b64_tr_b16 v[190:191], v251 offset:34816
	ds_read_b64_tr_b16 v[186:187], v147 offset:34816
	ds_read_b64_tr_b16 v[182:183], v148 offset:34816
	ds_read_b64_tr_b16 v[178:179], v149 offset:34816
	ds_read_b64_tr_b16 v[172:173], v251 offset:36864
	ds_read_b64_tr_b16 v[168:169], v147 offset:36864
	ds_read_b64_tr_b16 v[164:165], v148 offset:36864
	ds_read_b64_tr_b16 v[160:161], v149 offset:36864
	ds_read_b64_tr_b16 v[174:175], v251 offset:38912
	ds_read_b64_tr_b16 v[170:171], v147 offset:38912
	ds_read_b64_tr_b16 v[166:167], v148 offset:38912
	ds_read_b64_tr_b16 v[162:163], v149 offset:38912
	v_mfma_f32_32x32x16_bf16 v[112:127], v[218:221], v[140:143], v[112:127]
	s_waitcnt lgkmcnt(14)
	v_mfma_f32_32x32x16_bf16 v[96:111], v[230:233], v[140:143], v[96:111]
	s_nop 9
	v_max_f32_e32 v218, v127, v127
	s_nop 0
	v_max_f32_e32 v219, v111, v111
	v_max_f32_e32 v218, v219, v218
	v_max3_f32 v219, v218, v112, v96
	v_max3_f32 v218, v218, v113, v97
	s_nop 0
	v_max3_f32 v219, v219, v114, v98
	v_max3_f32 v218, v218, v115, v99
	s_nop 0
	v_max3_f32 v219, v219, v116, v100
	v_max3_f32 v218, v218, v117, v101
	s_nop 0
	v_max3_f32 v219, v219, v118, v102
	v_max3_f32 v218, v218, v119, v103
	s_nop 0
	v_max3_f32 v219, v219, v120, v104
	v_max3_f32 v218, v218, v121, v105
	s_nop 0
	v_max3_f32 v219, v219, v122, v106
	v_max3_f32 v218, v218, v123, v107
	s_nop 0
	v_max3_f32 v219, v219, v124, v108
	v_max3_f32 v218, v218, v125, v109
	s_nop 0
	v_max3_f32 v219, v219, v126, v110
	v_max3_f32 v218, v218, v127, v111
	s_nop 0
	v_max_f32_e32 v218, v218, v218
	v_max_f32_e32 v219, v219, v219
	v_max_f32_e32 v252, v219, v218
	v_cmp_lt_f32_e32 vcc, s31, v252
	s_cbranch_vccz .LBB0_193
	ds_bpermute_b32 v218, v197, v252
	s_waitcnt lgkmcnt(0)
	v_max3_f32 v218, v252, v218, 0
	v_exp_f32_e64 v220, -v218
	v_pk_add_f32 v[112:113], v[112:113], v[218:219] op_sel_hi:[1,0] neg_lo:[0,1] neg_hi:[0,1]
	v_pk_add_f32 v[96:97], v[96:97], v[218:219] op_sel_hi:[1,0] neg_lo:[0,1] neg_hi:[0,1]
	v_pk_add_f32 v[114:115], v[114:115], v[218:219] op_sel_hi:[1,0] neg_lo:[0,1] neg_hi:[0,1]
	v_pk_add_f32 v[98:99], v[98:99], v[218:219] op_sel_hi:[1,0] neg_lo:[0,1] neg_hi:[0,1]
	v_pk_add_f32 v[116:117], v[116:117], v[218:219] op_sel_hi:[1,0] neg_lo:[0,1] neg_hi:[0,1]
	v_pk_add_f32 v[100:101], v[100:101], v[218:219] op_sel_hi:[1,0] neg_lo:[0,1] neg_hi:[0,1]
	v_pk_add_f32 v[118:119], v[118:119], v[218:219] op_sel_hi:[1,0] neg_lo:[0,1] neg_hi:[0,1]
	v_pk_add_f32 v[102:103], v[102:103], v[218:219] op_sel_hi:[1,0] neg_lo:[0,1] neg_hi:[0,1]
	v_pk_add_f32 v[120:121], v[120:121], v[218:219] op_sel_hi:[1,0] neg_lo:[0,1] neg_hi:[0,1]
	v_pk_add_f32 v[104:105], v[104:105], v[218:219] op_sel_hi:[1,0] neg_lo:[0,1] neg_hi:[0,1]
	v_pk_add_f32 v[122:123], v[122:123], v[218:219] op_sel_hi:[1,0] neg_lo:[0,1] neg_hi:[0,1]
	v_pk_add_f32 v[106:107], v[106:107], v[218:219] op_sel_hi:[1,0] neg_lo:[0,1] neg_hi:[0,1]
	v_pk_add_f32 v[124:125], v[124:125], v[218:219] op_sel_hi:[1,0] neg_lo:[0,1] neg_hi:[0,1]
	v_pk_add_f32 v[108:109], v[108:109], v[218:219] op_sel_hi:[1,0] neg_lo:[0,1] neg_hi:[0,1]
	v_pk_add_f32 v[126:127], v[126:127], v[218:219] op_sel_hi:[1,0] neg_lo:[0,1] neg_hi:[0,1]
	v_pk_add_f32 v[110:111], v[110:111], v[218:219] op_sel_hi:[1,0] neg_lo:[0,1] neg_hi:[0,1]
	v_pk_mul_f32 v[94:95], v[94:95], v[220:221] op_sel_hi:[1,0]
	v_pk_mul_f32 v[92:93], v[92:93], v[220:221] op_sel_hi:[1,0]
	v_pk_mul_f32 v[90:91], v[90:91], v[220:221] op_sel_hi:[1,0]
	v_pk_mul_f32 v[88:89], v[88:89], v[220:221] op_sel_hi:[1,0]
	v_pk_mul_f32 v[86:87], v[86:87], v[220:221] op_sel_hi:[1,0]
	v_pk_mul_f32 v[84:85], v[84:85], v[220:221] op_sel_hi:[1,0]
; template <int KIND> ...
;     ...
;                     m_ref += d;
; #pragma unroll
;                     for (int j = 0; j < 16; ++j) { mneg[j] -= d; s0[j] -= d; s1[j] -= d; lacc[j] *= alpha; }
; #pragma unroll
;                     for (int dt = 0; dt < NDT; ++dt)
; #pragma unroll
;                         for (int j = 0; j < 16; ++j) o[dt][j] *= alpha;
	v_pk_mul_f32 v[82:83], v[82:83], v[220:221] op_sel_hi:[1,0]
	v_pk_mul_f32 v[80:81], v[80:81], v[220:221] op_sel_hi:[1,0]
	v_pk_mul_f32 v[62:63], v[62:63], v[220:221] op_sel_hi:[1,0]
	v_pk_mul_f32 v[60:61], v[60:61], v[220:221] op_sel_hi:[1,0]
	v_pk_mul_f32 v[58:59], v[58:59], v[220:221] op_sel_hi:[1,0]
	v_pk_mul_f32 v[56:57], v[56:57], v[220:221] op_sel_hi:[1,0]
	v_pk_mul_f32 v[54:55], v[54:55], v[220:221] op_sel_hi:[1,0]
	v_pk_mul_f32 v[52:53], v[52:53], v[220:221] op_sel_hi:[1,0]
	v_pk_mul_f32 v[50:51], v[50:51], v[220:221] op_sel_hi:[1,0]
	v_pk_mul_f32 v[48:49], v[48:49], v[220:221] op_sel_hi:[1,0]
	v_pk_mul_f32 v[46:47], v[46:47], v[220:221] op_sel_hi:[1,0]
	v_pk_mul_f32 v[44:45], v[44:45], v[220:221] op_sel_hi:[1,0]
	v_pk_mul_f32 v[42:43], v[42:43], v[220:221] op_sel_hi:[1,0]
	v_pk_mul_f32 v[40:41], v[40:41], v[220:221] op_sel_hi:[1,0]
	v_pk_mul_f32 v[38:39], v[38:39], v[220:221] op_sel_hi:[1,0]
	v_pk_mul_f32 v[36:37], v[36:37], v[220:221] op_sel_hi:[1,0]
	v_pk_mul_f32 v[34:35], v[34:35], v[220:221] op_sel_hi:[1,0]
	v_pk_mul_f32 v[32:33], v[32:33], v[220:221] op_sel_hi:[1,0]
	v_pk_mul_f32 v[30:31], v[30:31], v[220:221] op_sel_hi:[1,0]
	v_pk_mul_f32 v[28:29], v[28:29], v[220:221] op_sel_hi:[1,0]
	v_pk_mul_f32 v[26:27], v[26:27], v[220:221] op_sel_hi:[1,0]
	v_pk_mul_f32 v[24:25], v[24:25], v[220:221] op_sel_hi:[1,0]
	v_pk_mul_f32 v[22:23], v[22:23], v[220:221] op_sel_hi:[1,0]
	v_pk_mul_f32 v[20:21], v[20:21], v[220:221] op_sel_hi:[1,0]
	v_pk_mul_f32 v[18:19], v[18:19], v[220:221] op_sel_hi:[1,0]
	v_pk_mul_f32 v[16:17], v[16:17], v[220:221] op_sel_hi:[1,0]
	v_pk_mul_f32 v[14:15], v[14:15], v[220:221] op_sel_hi:[1,0]
	v_pk_mul_f32 v[12:13], v[12:13], v[220:221] op_sel_hi:[1,0]
	v_pk_mul_f32 v[10:11], v[10:11], v[220:221] op_sel_hi:[1,0]
	v_pk_mul_f32 v[8:9], v[8:9], v[220:221] op_sel_hi:[1,0]
	v_pk_mul_f32 v[6:7], v[6:7], v[220:221] op_sel_hi:[1,0]
	v_pk_mul_f32 v[4:5], v[4:5], v[220:221] op_sel_hi:[1,0]
	v_pk_mul_f32 v[2:3], v[2:3], v[220:221] op_sel_hi:[1,0]
	v_pk_mul_f32 v[0:1], v[0:1], v[220:221] op_sel_hi:[1,0]
	v_sub_f32_e32 v79, v79, v218
	v_sub_f32_e32 v78, v78, v218
	v_sub_f32_e32 v77, v77, v218
	v_sub_f32_e32 v76, v76, v218
	v_sub_f32_e32 v75, v75, v218
	v_sub_f32_e32 v74, v74, v218
	v_sub_f32_e32 v73, v73, v218
	v_sub_f32_e32 v72, v72, v218
	v_sub_f32_e32 v71, v71, v218
	v_sub_f32_e32 v70, v70, v218
	v_sub_f32_e32 v69, v69, v218
	v_sub_f32_e32 v68, v68, v218
	v_sub_f32_e32 v67, v67, v218
	v_sub_f32_e32 v66, v66, v218
	v_sub_f32_e32 v65, v65, v218
	v_sub_f32_e32 v64, v64, v218
; template <int KIND> ...
;     ...
; #pragma unroll
;                 for (int j = 0; j < 16; ++j) s0[j] = __builtin_amdgcn_exp2f(s0[j]);
;                 bf16x8 pf[4];
; #pragma unroll
;                 for (int s = 0; s < 2; ++s) { u32x4 w; w.x = pk2n(s0[8 * s + 0], s0[8 * s + 1]); w.y = pk2n(s0[8 * s + 2], s0[8 * s + 3]); w.z = pk2n(s0[8 * s + 4], s0[8 * s + 5]); w.w = pk2n(s0[8 * s + 6], s0[8 * s + 7]);
;                     pf[s] = __builtin_bit_cast(bf16x8, w); }
;                 __builtin_amdgcn_sched_barrier(0);
; #pragma unroll
;                 for (int s = 0; s < 2; ++s)
; #pragma unroll
;                     for (int dt = 0; dt < NDT; ++dt) {
;                         vfb[s][dt][0] = __builtin_amdgcn_ds_read_tr16_b64_v4i16((LAS s16x4*)(lds + buf * VBUF + voff + (16 * (s + 2)) * VSTR + 64 * dt));
;                         vfb[s][dt][1] = __builtin_amdgcn_ds_read_tr16_b64_v4i16((LAS s16x4*)(lds + buf * VBUF + voff + (16 * (s + 2) + 8) * VSTR + 64 * dt)); }
;                 {
;                     constexpr int NM = 2 * (1 + NDT);
;                     int mi = 0;
; #pragma unroll
;                     for (int s = 0; s < 2; ++s) {
;                         lacc = __builtin_amdgcn_mfma_f32_32x32x16_bf16(ones, pf[s], lacc, 0, 0, 0);
; #pragma unroll
;                         for (int j = (mi * 16) / NM; j < ((mi + 1) * 16) / NM; ++j) s1[j] = __builtin_amdgcn_exp2f(s1[j]);
;                         ++mi;
; #pragma unroll
;                         for (int dt = 0; dt < NDT; ++dt) {
;                             const s16x4 va = vfa[s][dt][0], vb = vfa[s][dt][1];
;                             const bf16x8 vf = {va[0], va[1], va[2], va[3], vb[0], vb[1], vb[2], vb[3]};
;                             o[dt] = __builtin_amdgcn_mfma_f32_32x32x16_bf16(vf, pf[s], o[dt], 0, 0, 0);
; #pragma unroll
;                             for (int j = (mi * 16) / NM; j < ((mi + 1) * 16) / NM; ++j) s1[j] = __builtin_amdgcn_exp2f(s1[j]);
;                             ++mi;
;                         }
;                     }
; #pragma unroll
;                     for (int q = 0; q < 2; ++q) { u32x4 w; w.x = pk2n(s1[8 * q + 0], s1[8 * q + 1]); w.y = pk2n(s1[8 * q + 2], s1[8 * q + 3]); w.z = pk2n(s1[8 * q + 4], s1[8 * q + 5]); w.w = pk2n(s1[8 * q + 6], s1[8 * q + 7]);
;                         pf[q + 2] = __builtin_bit_cast(bf16x8, w); }
; #pragma unroll
.LBB0_193:
	v_exp_f32_e32 v112, v112
	v_exp_f32_e32 v113, v113
	v_exp_f32_e32 v114, v114
	v_exp_f32_e32 v115, v115
	v_exp_f32_e32 v116, v116
	v_exp_f32_e32 v117, v117
	v_exp_f32_e32 v118, v118
	v_exp_f32_e32 v119, v119
	v_exp_f32_e32 v120, v120
	v_exp_f32_e32 v121, v121
	v_exp_f32_e32 v122, v122
	v_exp_f32_e32 v123, v123
	v_exp_f32_e32 v124, v124
	v_exp_f32_e32 v125, v125
	v_exp_f32_e32 v126, v126
	v_exp_f32_e32 v127, v127
	v_cvt_pk_bf16_f32 v112, v112, v113
	v_cvt_pk_bf16_f32 v113, v114, v115
	v_cvt_pk_bf16_f32 v114, v116, v117
	v_cvt_pk_bf16_f32 v115, v118, v119
	v_cvt_pk_bf16_f32 v116, v120, v121
	v_cvt_pk_bf16_f32 v117, v122, v123
	v_cvt_pk_bf16_f32 v118, v124, v125
	v_cvt_pk_bf16_f32 v119, v126, v127
	s_waitcnt lgkmcnt(11)
	v_mfma_f32_32x32x16_bf16 v[48:63], v[188:191], v[112:115], v[48:63]
	v_mov_b64_e32 v[122:123], s[86:87]
	v_mov_b64_e32 v[120:121], s[84:85]
	v_exp_f32_e32 v124, v96
	s_nop 0
	v_mfma_f32_32x32x16_bf16 v[80:95], v[120:123], v[112:115], v[80:95]
	v_exp_f32_e32 v125, v97
	v_exp_f32_e32 v98, v98
	v_exp_f32_e32 v99, v99
	ds_read_b64_tr_b16 v[96:97], v251 offset:40960
	s_waitcnt lgkmcnt(11)
	v_mfma_f32_32x32x16_bf16 v[32:47], v[184:187], v[112:115], v[32:47]
	v_exp_f32_e32 v126, v100
	v_exp_f32_e32 v127, v101
	v_exp_f32_e32 v184, v102
	s_waitcnt lgkmcnt(10)
	v_mfma_f32_32x32x16_bf16 v[16:31], v[180:183], v[112:115], v[16:31]
	v_exp_f32_e32 v103, v103
	v_exp_f32_e32 v185, v104
	v_exp_f32_e32 v180, v105
	ds_read_b64_tr_b16 v[104:105], v147 offset:40960
	s_waitcnt lgkmcnt(10)
	v_mfma_f32_32x32x16_bf16 v[0:15], v[176:179], v[112:115], v[0:15]
	v_exp_f32_e32 v181, v106
	v_exp_f32_e32 v182, v107
	v_exp_f32_e32 v114, v108
	ds_read_b64_tr_b16 v[106:107], v147 offset:43008
	ds_read_b64_tr_b16 v[178:179], v149 offset:47104
	v_mfma_f32_32x32x16_bf16 v[80:95], v[120:123], v[116:119], v[80:95]
	v_exp_f32_e32 v115, v109
	v_exp_f32_e32 v176, v110
	v_exp_f32_e32 v177, v111
	ds_read_b64_tr_b16 v[108:109], v148 offset:40960
	ds_read_b64_tr_b16 v[110:111], v148 offset:43008
	s_waitcnt lgkmcnt(9)
	v_mfma_f32_32x32x16_bf16 v[48:63], v[172:175], v[116:119], v[48:63]
	v_cvt_pk_bf16_f32 v100, v124, v125
	v_cvt_pk_bf16_f32 v101, v98, v99
	v_cvt_pk_bf16_f32 v102, v126, v127
	ds_read_b64_tr_b16 v[98:99], v251 offset:43008
	ds_read_b64_tr_b16 v[124:125], v149 offset:40960
	ds_read_b64_tr_b16 v[126:127], v149 offset:43008
	ds_read_b64_tr_b16 v[172:173], v148 offset:45056
	s_waitcnt lgkmcnt(12)
	v_mfma_f32_32x32x16_bf16 v[32:47], v[168:171], v[116:119], v[32:47]
	v_cvt_pk_bf16_f32 v103, v184, v103
	v_cvt_pk_bf16_f32 v112, v185, v180
	v_cvt_pk_bf16_f32 v113, v181, v182
	ds_read_b64_tr_b16 v[168:169], v251 offset:45056
	ds_read_b64_tr_b16 v[170:171], v251 offset:47104
	ds_read_b64_tr_b16 v[174:175], v148 offset:47104
	s_waitcnt lgkmcnt(14)
	v_mfma_f32_32x32x16_bf16 v[16:31], v[164:167], v[116:119], v[16:31]
	v_cvt_pk_bf16_f32 v114, v114, v115
	v_cvt_pk_bf16_f32 v115, v176, v177
	ds_read_b64_tr_b16 v[164:165], v147 offset:45056
	ds_read_b64_tr_b16 v[166:167], v147 offset:47104
	ds_read_b64_tr_b16 v[176:177], v149 offset:45056
	s_waitcnt lgkmcnt(14)
	v_mfma_f32_32x32x16_bf16 v[0:15], v[160:163], v[116:119], v[0:15]
	s_andn2_b64 vcc, exec, s[4:5]
	s_cbranch_vccnz .Ldf4_y2_plain
	s_and_b32 s29, s17, 1
	s_lshl_b32 s29, s29, 14
	v_add_u32_e32 v150, s29, v235
	v_xor_b32_e32 v151, 32, v150
	v_xor_b32_e32 v152, 64, v150
	v_xor_b32_e32 v153, 0x60, v150
	s_waitcnt lgkmcnt(12)
	ds_read_b128 v[160:163], v151
	ds_read_b128 v[218:221], v153
	ds_read_b128 v[230:233], v153 offset:4096
	v_mfma_f32_32x32x16_bf16 v[80:95], v[120:123], v[100:103], v[80:95]
	s_waitcnt lgkmcnt(12)
	v_mfma_f32_32x32x16_bf16 v[48:63], v[96:99], v[100:103], v[48:63]
	ds_read_b128 v[96:99], v150
	v_mfma_f32_32x32x16_bf16 v[32:47], v[104:107], v[100:103], v[32:47]
	v_mfma_f32_32x32x16_bf16 v[16:31], v[108:111], v[100:103], v[16:31]
	s_waitcnt lgkmcnt(11)
	v_mfma_f32_32x32x16_bf16 v[0:15], v[124:127], v[100:103], v[0:15]
	v_mfma_f32_32x32x16_bf16 v[80:95], v[120:123], v[112:115], v[80:95]
	s_waitcnt lgkmcnt(8)
	v_mfma_f32_32x32x16_bf16 v[48:63], v[168:171], v[112:115], v[48:63]
	ds_read_b128 v[168:171], v151 offset:4096
	s_waitcnt lgkmcnt(6)
	v_mfma_f32_32x32x16_bf16 v[32:47], v[164:167], v[112:115], v[32:47]
	ds_read_b128 v[164:167], v150 offset:4096
	v_mfma_f32_32x32x16_bf16 v[16:31], v[172:175], v[112:115], v[16:31]
	ds_read_b128 v[172:175], v152
	s_waitcnt lgkmcnt(7)
	v_mfma_f32_32x32x16_bf16 v[0:15], v[176:179], v[112:115], v[0:15]
	ds_read_b128 v[176:179], v152 offset:4096
	s_branch .LBB0_188
